# v32 + gMLP spatial-gating k-loop: all W fragments preloaded, loop unrolled with early exit (no per-step load wait)
# baseline (speedup 1.0000x reference)
; #define LAS __attribute__((address_space(3)))
; DI s16x4 vtr(const LAS char* p) { return __builtin_bit_cast(s16x4, __builtin_amdgcn_ds_read_tr16_b64_v4i16((LAS v4i16_t*)p)); }
; #define MFMA32(a, b, c) __builtin_amdgcn_mfma_f32_32x32x16_bf16((a), (b), (c), 0, 0, 0)
; DI bf16x8 cat8(s16x4 lo, s16x4 hi) { return __builtin_shufflevector(lo, hi, 0, 1, 2, 3, 4, 5, 6, 7); }
; DI void phase_sgu(ArgsP AP, LAS unsigned char* lds) {
;     ...
;             const bf16* wrow = WST + ((size_t)g * 128 + 32 * tb + r32) * 128 + 8 * h;
;             for (int ks = 0; ks < 2 * tb + 2; ++ks) {
;                 const bf16x8 a = *(const bf16x8*)(wrow + 16 * ks);
; #pragma unroll
;                 for (int ci = 0; ci < 2; ++ci) {
;                     const LAS char* p = vl + (16 * ks + 8 * h + (i16 >> 2)) * 288 + (32 * (cb0 + ci) + 16 * blk + 4 * (i16 & 3)) * 2;
;                     const s16x4 lo = vtr(p), hi = vtr(p + 4 * 288);
;                     acc[ci] = MFMA32(a, cat8(lo, hi), acc[ci]);
;                 }
;             }
.LBB0_234:
	global_load_dwordx4 v[98:101], v[32:33], off
	global_load_dwordx4 v[102:105], v[32:33], off offset:32
	global_load_dwordx4 v[106:109], v[32:33], off offset:64
	global_load_dwordx4 v[110:113], v[32:33], off offset:96
	global_load_dwordx4 v[114:117], v[32:33], off offset:128
	global_load_dwordx4 v[118:121], v[32:33], off offset:160
	global_load_dwordx4 v[122:125], v[32:33], off offset:192
	global_load_dwordx4 v[126:129], v[32:33], off offset:224
	v_add_u32_e32 v35, 0xfffffb40, v34
	ds_read_b64_tr_b16 v[92:93], v35
	v_subrev_u32_e32 v35, 64, v34
	ds_read_b64_tr_b16 v[94:95], v35
	v_add_u32_e32 v35, 0xfffffb80, v34
	s_add_i32 s3, s3, -1
	s_cmp_eq_u32 s3, 0
	s_waitcnt vmcnt(7) lgkmcnt(0)
	v_mfma_f32_32x32x16_bf16 v[16:31], v[98:101], v[92:95], v[16:31]
	ds_read_b64_tr_b16 v[92:93], v35
	ds_read_b64_tr_b16 v[94:95], v34
	v_add_u32_e32 v34, 0x1200, v34
	s_waitcnt lgkmcnt(0)
	v_mfma_f32_32x32x16_bf16 v[0:15], v[98:101], v[92:95], v[0:15]
	s_cbranch_scc1 .Lsgu_kdone
	v_add_u32_e32 v35, 0xfffffb40, v34
	ds_read_b64_tr_b16 v[92:93], v35
	v_subrev_u32_e32 v35, 64, v34
	ds_read_b64_tr_b16 v[94:95], v35
	v_add_u32_e32 v35, 0xfffffb80, v34
	s_add_i32 s3, s3, -1
	s_cmp_eq_u32 s3, 0
	s_waitcnt vmcnt(6) lgkmcnt(0)
	v_mfma_f32_32x32x16_bf16 v[16:31], v[102:105], v[92:95], v[16:31]
	ds_read_b64_tr_b16 v[92:93], v35
	ds_read_b64_tr_b16 v[94:95], v34
	v_add_u32_e32 v34, 0x1200, v34
	s_waitcnt lgkmcnt(0)
	v_mfma_f32_32x32x16_bf16 v[0:15], v[102:105], v[92:95], v[0:15]
	s_cbranch_scc1 .Lsgu_kdone
	v_add_u32_e32 v35, 0xfffffb40, v34
	ds_read_b64_tr_b16 v[92:93], v35
	v_subrev_u32_e32 v35, 64, v34
	ds_read_b64_tr_b16 v[94:95], v35
	v_add_u32_e32 v35, 0xfffffb80, v34
	s_add_i32 s3, s3, -1
	s_cmp_eq_u32 s3, 0
	s_waitcnt vmcnt(5) lgkmcnt(0)
	v_mfma_f32_32x32x16_bf16 v[16:31], v[106:109], v[92:95], v[16:31]
	ds_read_b64_tr_b16 v[92:93], v35
	ds_read_b64_tr_b16 v[94:95], v34
	v_add_u32_e32 v34, 0x1200, v34
	s_waitcnt lgkmcnt(0)
	v_mfma_f32_32x32x16_bf16 v[0:15], v[106:109], v[92:95], v[0:15]
	s_cbranch_scc1 .Lsgu_kdone
	v_add_u32_e32 v35, 0xfffffb40, v34
	ds_read_b64_tr_b16 v[92:93], v35
	v_subrev_u32_e32 v35, 64, v34
	ds_read_b64_tr_b16 v[94:95], v35
	v_add_u32_e32 v35, 0xfffffb80, v34
	s_add_i32 s3, s3, -1
	s_cmp_eq_u32 s3, 0
	s_waitcnt vmcnt(4) lgkmcnt(0)
	v_mfma_f32_32x32x16_bf16 v[16:31], v[110:113], v[92:95], v[16:31]
	ds_read_b64_tr_b16 v[92:93], v35
	ds_read_b64_tr_b16 v[94:95], v34
	v_add_u32_e32 v34, 0x1200, v34
	s_waitcnt lgkmcnt(0)
	v_mfma_f32_32x32x16_bf16 v[0:15], v[110:113], v[92:95], v[0:15]
	s_cbranch_scc1 .Lsgu_kdone
	v_add_u32_e32 v35, 0xfffffb40, v34
	ds_read_b64_tr_b16 v[92:93], v35
	v_subrev_u32_e32 v35, 64, v34
	ds_read_b64_tr_b16 v[94:95], v35
	v_add_u32_e32 v35, 0xfffffb80, v34
	s_add_i32 s3, s3, -1
	s_cmp_eq_u32 s3, 0
	s_waitcnt vmcnt(3) lgkmcnt(0)
	v_mfma_f32_32x32x16_bf16 v[16:31], v[114:117], v[92:95], v[16:31]
	ds_read_b64_tr_b16 v[92:93], v35
	ds_read_b64_tr_b16 v[94:95], v34
	v_add_u32_e32 v34, 0x1200, v34
	s_waitcnt lgkmcnt(0)
	v_mfma_f32_32x32x16_bf16 v[0:15], v[114:117], v[92:95], v[0:15]
	s_cbranch_scc1 .Lsgu_kdone
	v_add_u32_e32 v35, 0xfffffb40, v34
	ds_read_b64_tr_b16 v[92:93], v35
	v_subrev_u32_e32 v35, 64, v34
	ds_read_b64_tr_b16 v[94:95], v35
	v_add_u32_e32 v35, 0xfffffb80, v34
	s_add_i32 s3, s3, -1
	s_cmp_eq_u32 s3, 0
	s_waitcnt vmcnt(2) lgkmcnt(0)
	v_mfma_f32_32x32x16_bf16 v[16:31], v[118:121], v[92:95], v[16:31]
	ds_read_b64_tr_b16 v[92:93], v35
	ds_read_b64_tr_b16 v[94:95], v34
	v_add_u32_e32 v34, 0x1200, v34
	s_waitcnt lgkmcnt(0)
	v_mfma_f32_32x32x16_bf16 v[0:15], v[118:121], v[92:95], v[0:15]
	s_cbranch_scc1 .Lsgu_kdone
	v_add_u32_e32 v35, 0xfffffb40, v34
	ds_read_b64_tr_b16 v[92:93], v35
	v_subrev_u32_e32 v35, 64, v34
	ds_read_b64_tr_b16 v[94:95], v35
	v_add_u32_e32 v35, 0xfffffb80, v34
	s_add_i32 s3, s3, -1
	s_cmp_eq_u32 s3, 0
	s_waitcnt vmcnt(1) lgkmcnt(0)
	v_mfma_f32_32x32x16_bf16 v[16:31], v[122:125], v[92:95], v[16:31]
	ds_read_b64_tr_b16 v[92:93], v35
	ds_read_b64_tr_b16 v[94:95], v34
	v_add_u32_e32 v34, 0x1200, v34
	s_waitcnt lgkmcnt(0)
	v_mfma_f32_32x32x16_bf16 v[0:15], v[122:125], v[92:95], v[0:15]
	s_cbranch_scc1 .Lsgu_kdone
	v_add_u32_e32 v35, 0xfffffb40, v34
	ds_read_b64_tr_b16 v[92:93], v35
	v_subrev_u32_e32 v35, 64, v34
	ds_read_b64_tr_b16 v[94:95], v35
	v_add_u32_e32 v35, 0xfffffb80, v34
	s_add_i32 s3, s3, -1
	s_cmp_eq_u32 s3, 0
	s_waitcnt vmcnt(0) lgkmcnt(0)
	v_mfma_f32_32x32x16_bf16 v[16:31], v[126:129], v[92:95], v[16:31]
	ds_read_b64_tr_b16 v[92:93], v35
	ds_read_b64_tr_b16 v[94:95], v34
	v_add_u32_e32 v34, 0x1200, v34
	s_waitcnt lgkmcnt(0)
	v_mfma_f32_32x32x16_bf16 v[0:15], v[126:129], v[92:95], v[0:15]
.Lsgu_kdone:
	s_waitcnt vmcnt(0)
	s_branch .LBB0_221
